# v40 + nt cache policy on the once-read streams of phase 16: attention query-fragment loads and the LRU backward pass's forward-state / gate loads
# baseline (speedup 1.0000x reference)
; #define LAS __attribute__((address_space(3)))
; __device__ __forceinline__ void attn_wave_unit(const Params& p, const LAS float* rpbh, const LAS u32x4* ckL, const LAS u32x4* cvL, const LAS u32x4* ringL, LAS u32x4* qL, int b, int h, int r, int qg, int lane) {
;     const bf16* ZO = (const bf16*)(p.ws + WS_Z); const u32x2* VF = (const u32x2*)(p.ws + WS_VT); bf16* MIX = (bf16*)(p.ws + WS_MIX);
;     const int l15 = lane & 15, g = lane >> 4;
;     const int c0 = 16 * qg, qc = c0 + l15, qrow = b * SEQ + r * GW + qc;
;     const int r0 = min(max(r - WIN_R / 2, 0), GROWS - WIN_R);
;     const int kb = qg == 0 ? 0 : (qg == 1 ? 8 : (qg == 2 ? 24 : 32));
;     const int cs = min(max(qc - WIN_C / 2, 0), GW - WIN_C);
; #pragma unroll
;     for (int kk = 0; kk < 2; ++kk) qL[kk * 64 + lane] = *(const u32x4*)(ZO + (size_t)qrow * ZO_LD + h * HD + 8 * g + 32 * kk);
;     ...
;     unsigned dcol[4];
; #pragma unroll
;     for (int j = 0; j < 8; ++j) { const int a = j >> 2, e = j & 3, kc = kb + 16 * a + 4 * g + e; const unsigned dc = ((kc >= cs) && (kc < cs + WIN_C)) ? (unsigned)(kc - qc + WIN_C - 1) : 465u;
;         if (j & 1) dcol[j >> 1] |= dc << 16; else dcol[j >> 1] = dc; }
;     const bool mis = (kb & 8) != 0;
;     const unsigned klo_ctx = (unsigned)(g * 16 + l15), klo_ring = (unsigned)((kb >> 4) * 128) + (mis ? (unsigned)(((l15 + 8) >> 4) * 128 + g * 16 + ((l15 + 8) & 15)) : klo_ctx);
;     const unsigned vlo_ctx = (unsigned)(g * 16 + l15), vlo_loc = mis ? (unsigned)(((4 * g + 8) >> 4) * 4096 + (((4 * g + 8) >> 2) & 3) * 16 + l15) : vlo_ctx;
;     u32x4 vx[4][4];
;     ...
;     f32x4 o[4];
; #pragma unroll
;     for (int d = 0; d < 4; ++d) o[d] = (f32x4){0.f, 0.f, 0.f, 0.f};
;     float mrun = -1e30f, lsum = 0.f;
;     ATT_LOADV(2);
.LBB0_2217:
	s_lshl_b32 s0, s6, 3
	s_add_i32 s0, s0, s96
	s_lshr_b32 s67, s0, 2
	v_and_b32_e32 v138, 15, v128
	s_lshl_b32 s65, s67, 6
	v_sub_u32_e64 v2, s67, 4 clamp
	v_or_b32_e32 v137, s41, v138
	s_add_i32 s65, s65, s57
	v_readfirstlane_b32 s0, v2
	s_lshl_b32 s24, s4, 6
	v_or_b32_e32 v4, s65, v137
	s_min_u32 s68, s0, 24
	v_mov_b64_e32 v[2:3], s[84:85]
	s_ashr_i32 s25, s24, 31
	v_ashrrev_i32_e32 v6, 4, v128
	v_mad_u64_u32 v[2:3], s[0:1], v4, s54, v[2:3]
	s_bitcmp0_b32 s66, 3
	v_lshlrev_b32_e32 v4, 3, v6
	s_cselect_b64 s[0:1], -1, 0
	s_lshl_b32 s6, s4, 8
	v_lshl_add_u64 v[2:3], s[24:25], 1, v[2:3]
	v_ashrrev_i32_e32 v5, 31, v4
	s_ashr_i32 s7, s6, 31
	v_lshl_add_u64 v[2:3], v[4:5], 1, v[2:3]
	v_lshlrev_b32_e32 v139, 2, v6
	s_lshl_b64 s[6:7], s[6:7], 3
	global_load_dwordx4 v[14:17], v[2:3], off nt
	global_load_dwordx4 v[34:37], v[2:3], off offset:64 nt
	v_add_u32_e32 v2, 8, v139
	s_add_u32 s6, s28, s6
	v_lshlrev_b32_e32 v3, 8, v2
	v_lshlrev_b32_e32 v2, 2, v2
	s_addc_u32 s7, s29, s7
	s_lshl_b32 s4, s68, 6
	v_and_b32_e32 v3, 0xfffff000, v3
	v_and_b32_e32 v2, 48, v2
	s_or_b32 s4, s4, s57
	v_or3_b32 v2, v3, v2, v138
	s_or_b32 s69, s66, s4
	v_cndmask_b32_e64 v126, v2, v128, s[0:1]
	s_lshr_b32 s4, s69, 4
	v_lshl_add_u64 v[130:131], v[126:127], 3, s[6:7]
	s_lshl_b64 s[6:7], s[4:5], 15
	s_add_i32 s4, s4, 1
	v_lshl_add_u64 v[2:3], v[130:131], 0, s[6:7]
	s_lshl_b64 s[6:7], s[4:5], 15
	s_add_i32 s4, s69, 64
	global_load_dwordx2 v[42:43], v[2:3], off
	global_load_dwordx2 v[22:23], v[2:3], off offset:512
	global_load_dwordx2 v[10:11], v[2:3], off offset:1024
	global_load_dwordx2 v[6:7], v[2:3], off offset:1536
	v_lshl_add_u64 v[2:3], v[130:131], 0, s[6:7]
	s_ashr_i32 s6, s4, 4
	s_ashr_i32 s7, s6, 31
	s_lshl_b64 s[6:7], s[6:7], 15
	s_add_i32 s4, s69, 0x80
	v_lshl_add_u64 v[4:5], v[130:131], 0, s[6:7]
	s_ashr_i32 s6, s4, 4
	s_ashr_i32 s7, s6, 31
	s_lshl_b64 s[6:7], s[6:7], 15
	s_add_i32 s4, s69, 0xc0
	global_load_dwordx2 v[44:45], v[2:3], off
	global_load_dwordx2 v[24:25], v[2:3], off offset:512
	global_load_dwordx2 v[12:13], v[2:3], off offset:1024
	global_load_dwordx2 v[8:9], v[2:3], off offset:1536
	global_load_dwordx2 v[62:63], v[4:5], off
	global_load_dwordx2 v[46:47], v[4:5], off offset:512
	global_load_dwordx2 v[26:27], v[4:5], off offset:1024
	s_nop 0
	global_load_dwordx2 v[2:3], v[4:5], off offset:1536
	s_waitcnt vmcnt(30)
	v_lshl_add_u64 v[18:19], v[4:5], 0, s[20:21]
	v_add_co_u32_e32 v4, vcc, s55, v4
	s_waitcnt vmcnt(26)
	v_lshl_add_u64 v[20:21], v[130:131], 0, s[6:7]
	s_ashr_i32 s6, s4, 4
	v_addc_co_u32_e32 v5, vcc, 0, v5, vcc
	s_ashr_i32 s7, s6, 31
	global_load_dwordx2 v[64:65], v[4:5], off
	global_load_dwordx2 v[48:49], v[18:19], off offset:512
	global_load_dwordx2 v[28:29], v[18:19], off offset:1024
	s_nop 0
	global_load_dwordx2 v[4:5], v[18:19], off offset:1536
	global_load_dwordx2 v[70:71], v[20:21], off
	global_load_dwordx2 v[58:59], v[20:21], off offset:512
	global_load_dwordx2 v[38:39], v[20:21], off offset:1024
	s_nop 0
	global_load_dwordx2 v[18:19], v[20:21], off offset:1536
	s_waitcnt vmcnt(30)
	v_lshl_add_u64 v[30:31], v[20:21], 0, s[20:21]
	v_add_co_u32_e32 v20, vcc, s55, v20
	s_lshl_b64 s[6:7], s[6:7], 15
	s_nop 0
	v_addc_co_u32_e32 v21, vcc, 0, v21, vcc
	s_waitcnt vmcnt(26)
	v_lshl_add_u64 v[32:33], v[130:131], 0, s[6:7]
	global_load_dwordx2 v[72:73], v[20:21], off
	global_load_dwordx2 v[60:61], v[30:31], off offset:512
	global_load_dwordx2 v[40:41], v[30:31], off offset:1024
	s_nop 0
	global_load_dwordx2 v[20:21], v[30:31], off offset:1536
	global_load_dwordx2 v[78:79], v[32:33], off
	global_load_dwordx2 v[66:67], v[32:33], off offset:512
	global_load_dwordx2 v[54:55], v[32:33], off offset:1024
	s_nop 0
	global_load_dwordx2 v[30:31], v[32:33], off offset:1536
	v_lshl_add_u64 v[50:51], v[32:33], 0, s[20:21]
	v_add_co_u32_e32 v32, vcc, 0x8000, v32
	v_mov_b32_e32 v136, 0
	s_nop 0
	v_addc_co_u32_e32 v33, vcc, 0, v33, vcc
	global_load_dwordx2 v[80:81], v[32:33], off
	global_load_dwordx2 v[68:69], v[50:51], off offset:512
	global_load_dwordx2 v[56:57], v[50:51], off offset:1024
	s_nop 0
	global_load_dwordx2 v[32:33], v[50:51], off offset:1536
	v_lshlrev_b32_e32 v50, 4, v128
	v_add_u32_e32 v126, s39, v50
	s_mov_b32 s4, 0
	s_waitcnt vmcnt(33)
	ds_write_b128 v126, v[14:17]
	s_waitcnt vmcnt(32)
	ds_write_b128 v126, v[34:37] offset:1024
	v_add_u32_e32 v140, 0, v50
	s_mov_b64 s[6:7], -1
	v_mov_b32_e32 v129, 0xf149f2ca
	v_mov_b32_e32 v14, 0
	v_mov_b32_e32 v15, v136
	v_mov_b32_e32 v16, v136
	v_mov_b32_e32 v17, v136
	v_mov_b32_e32 v34, 0
	v_mov_b32_e32 v35, v136
	v_mov_b32_e32 v36, v136
	v_mov_b32_e32 v37, v136
	v_mov_b32_e32 v50, 0
	v_mov_b32_e32 v51, v136
	v_mov_b32_e32 v52, v136
	v_mov_b32_e32 v53, v136
	v_mov_b32_e32 v74, 0
	v_mov_b32_e32 v75, v136
	v_mov_b32_e32 v76, v136
	v_mov_b32_e32 v77, v136
